# v32 + diff loops: step-1 QK^T scores in own registers, QK^T/PV MFMAs interleaved
# baseline (speedup 1.0000x reference)
; #define LAS __attribute__((address_space(3)))
; DI void expsum(f32x16& p, float& l_reg, bf16x8& pa0, bf16x8& pa1) {
; #pragma unroll
;     for (int r = 0; r < 16; ++r) p[r] = __builtin_amdgcn_exp2f(p[r]);
;     float ps = 0.f;
; #pragma unroll
;     for (int r = 0; r < 16; ++r) ps += p[r];
;     l_reg += ps; asm volatile("" : "+v"(l_reg));
;     ...
;     ATT_PK4(p, 0, pa0); ATT_PK4(p, 8, pa1);
;     ...
; }
; DI int v_rd_base(int lane) { return ((lane & 3) << 3) | (((lane >> 2) & 3) << 6) | (((lane >> 4) & 1) << 5) | (((lane >> 5) & 1) << 8); }
; template <int OFF> DI s16x4 tr_read(int vb) { s16x4 r; asm volatile("ds_read_b64_tr_b16 %0, %1 offset:%2" : "=&v"(r) : "v"(vb), "i"(OFF) : "memory"); return r; }
; template <int H> DI void v_reads(s16x4* vf, int vb) {
;     vf[0] = tr_read<v_rd_off(0, 2 * H, 0)>(vb); vf[1] = tr_read<v_rd_off(0, 2 * H, 1)>(vb); vf[2] = tr_read<v_rd_off(0, 2 * H + 1, 0)>(vb); vf[3] = tr_read<v_rd_off(0, 2 * H + 1, 1)>(vb);
;     vf[4] = tr_read<v_rd_off(1, 2 * H, 0)>(vb); vf[5] = tr_read<v_rd_off(1, 2 * H, 1)>(vb); vf[6] = tr_read<v_rd_off(1, 2 * H + 1, 0)>(vb); vf[7] = tr_read<v_rd_off(1, 2 * H + 1, 1)>(vb);
;     vf[8] = tr_read<v_rd_off(2, 2 * H, 0)>(vb); vf[9] = tr_read<v_rd_off(2, 2 * H, 1)>(vb); vf[10] = tr_read<v_rd_off(2, 2 * H + 1, 0)>(vb); vf[11] = tr_read<v_rd_off(2, 2 * H + 1, 1)>(vb);
;     vf[12] = tr_read<v_rd_off(3, 2 * H, 0)>(vb); vf[13] = tr_read<v_rd_off(3, 2 * H, 1)>(vb); vf[14] = tr_read<v_rd_off(3, 2 * H + 1, 0)>(vb); vf[15] = tr_read<v_rd_off(3, 2 * H + 1, 1)>(vb);
; }
; DI void pv_mma(f32x16* o, const s16x4* vf, bf16x8 pa0, bf16x8 pa1) {
;     ...
; #pragma unroll
;     for (int d0 = 0; d0 < 4; ++d0) {
;         o[d0] = __builtin_amdgcn_mfma_f32_32x32x16_bf16(pa0, ATT_PK(vf[4 * d0], vf[4 * d0 + 1]), o[d0], 0, 0, 0);
;         o[d0] = __builtin_amdgcn_mfma_f32_32x32x16_bf16(pa1, ATT_PK(vf[4 * d0 + 2], vf[4 * d0 + 3]), o[d0], 0, 0, 0); }
;     ...
; }
; template <int DQK, int D0A, int D0B> DI void k_reads(bf16x8* kf, const LAS unsigned char* Ks, int half, int r32, int hi) {
; #pragma unroll
;     for (int d0 = D0A; d0 < D0B; ++d0) kf[d0 - D0A] = *(const LAS bf16x8*)(Ks + half * (32 * DQK * 2) + kswz<DQK>(r32, (d0 * 16 + hi * 8) * 2));
; }
; template <int D0A, int D0B> DI void qk_mma(f32x16& p, const bf16x8* kf, const bf16x8* qr) {
; #pragma unroll
;     for (int d0 = D0A; d0 < D0B; ++d0) {
.LBB0_1922:
	s_add_i32 s3, s0, -1
	s_add_i32 s2, s22, 0xffffa000
	s_and_b32 s2, s2, 0x6000
	v_add_u32_e32 v121, s2, v114
	v_add_u32_e32 v122, v121, v115
	v_add_u32_e32 v126, v121, v116
	ds_read_b128 v[122:125], v122 offset:4096
	ds_read_b128 v[132:135], v126 offset:4096
	v_add_u32_e32 v126, v121, v117
	v_add_u32_e32 v121, v121, v118
	s_lshl_b32 s2, s1, 14
	ds_read_b128 v[136:139], v126 offset:4096
	ds_read_b128 v[140:143], v121 offset:4096
	v_add_u32_e32 v121, s2, v106
	ds_read_b64_tr_b16 v[144:145], v121 offset:0
	ds_read_b64_tr_b16 v[146:147], v121 offset:0x800
	ds_read_b64_tr_b16 v[148:149], v121 offset:0x1000
	ds_read_b64_tr_b16 v[150:151], v121 offset:0x1800
	ds_read_b64_tr_b16 v[152:153], v121 offset:0x200
	ds_read_b64_tr_b16 v[154:155], v121 offset:0xa00
	ds_read_b64_tr_b16 v[156:157], v121 offset:0x1200
	ds_read_b64_tr_b16 v[158:159], v121 offset:0x1a00
	ds_read_b64_tr_b16 v[162:163], v121 offset:0x400
	ds_read_b64_tr_b16 v[164:165], v121 offset:0xc00
	ds_read_b64_tr_b16 v[166:167], v121 offset:0x1400
	ds_read_b64_tr_b16 v[168:169], v121 offset:0x1c00
	ds_read_b64_tr_b16 v[170:171], v121 offset:0x600
	ds_read_b64_tr_b16 v[172:173], v121 offset:0xe00
	ds_read_b64_tr_b16 v[174:175], v121 offset:0x1600
	ds_read_b64_tr_b16 v[176:177], v121 offset:0x1e00
	s_setprio 1
	v_exp_f32_e32 v64, v64
	v_exp_f32_e32 v65, v65
	v_exp_f32_e32 v66, v66
	v_exp_f32_e32 v67, v67
	v_exp_f32_e32 v68, v68
	v_add_f32_e32 v126, 0, v64
	v_exp_f32_e32 v69, v69
	v_add_f32_e32 v126, v65, v126
	v_exp_f32_e32 v70, v70
	v_add_f32_e32 v126, v66, v126
	v_exp_f32_e32 v71, v71
	v_add_f32_e32 v126, v67, v126
	v_exp_f32_e32 v72, v72
	v_add_f32_e32 v126, v68, v126
	v_exp_f32_e32 v73, v73
	v_add_f32_e32 v126, v69, v126
	v_exp_f32_e32 v74, v74
	v_add_f32_e32 v126, v70, v126
	v_exp_f32_e32 v75, v75
	v_add_f32_e32 v126, v71, v126
	v_exp_f32_e32 v76, v76
	v_add_f32_e32 v126, v72, v126
	v_exp_f32_e32 v77, v77
	v_add_f32_e32 v126, v73, v126
	v_exp_f32_e32 v78, v78
	v_add_f32_e32 v126, v74, v126
	v_exp_f32_e32 v79, v79
	v_add_f32_e32 v126, v75, v126
	v_add_f32_e32 v126, v76, v126
	v_add_f32_e32 v126, v77, v126
	v_add_f32_e32 v126, v78, v126
	v_add_f32_e32 v126, v79, v126
	v_add_f32_e32 v120, v126, v120
	v_cvt_pk_bf16_f32 v64, v64, v65
	v_cvt_pk_bf16_f32 v65, v66, v67
	v_cvt_pk_bf16_f32 v66, v68, v69
	v_cvt_pk_bf16_f32 v67, v70, v71
	v_cvt_pk_bf16_f32 v68, v72, v73
	v_cvt_pk_bf16_f32 v69, v74, v75
	v_cvt_pk_bf16_f32 v70, v76, v77
	v_cvt_pk_bf16_f32 v71, v78, v79
	s_nop 0
	v_permlane32_swap_b32_e32 v64, v66
	v_permlane32_swap_b32_e32 v65, v67
	v_permlane32_swap_b32_e32 v68, v70
	v_permlane32_swap_b32_e32 v69, v71
	s_waitcnt lgkmcnt(0)
	s_setprio 0
	v_mfma_f32_32x32x16_bf16 v[0:15], v[64:67], v[144:147], v[0:15]
	s_cmp_lt_i32 s3, s55
	s_cselect_b64 vcc, -1, 0
	s_cmp_ge_i32 s3, s97
	s_cselect_b64 s[74:75], -1, 0
	s_or_b64 s[74:75], vcc, s[74:75]
	s_and_b64 vcc, exec, s[74:75]
	v_mfma_f32_32x32x16_bf16 v[180:195], v[122:125], v[92:95], 0
	v_mfma_f32_32x32x16_bf16 v[48:63], v[64:67], v[152:155], v[48:63]
	v_mfma_f32_32x32x16_bf16 v[180:195], v[132:135], v[88:91], v[180:195]
	v_mfma_f32_32x32x16_bf16 v[32:47], v[64:67], v[162:165], v[32:47]
	v_mfma_f32_32x32x16_bf16 v[180:195], v[136:139], v[84:87], v[180:195]
	v_mfma_f32_32x32x16_bf16 v[16:31], v[64:67], v[170:173], v[16:31]
	v_mfma_f32_32x32x16_bf16 v[180:195], v[140:143], v[80:83], v[180:195]
	v_mfma_f32_32x32x16_bf16 v[0:15], v[68:71], v[148:151], v[0:15]
	v_mfma_f32_32x32x16_bf16 v[48:63], v[68:71], v[156:159], v[48:63]
	v_mfma_f32_32x32x16_bf16 v[32:47], v[68:71], v[166:169], v[32:47]
	v_mfma_f32_32x32x16_bf16 v[16:31], v[68:71], v[174:177], v[16:31]
	v_add_u32_e32 v122, s7, v119
	s_cbranch_vccnz .LBB0_1924
	v_add_u32_e32 v138, 0x28908, v122
	v_add_u32_e32 v140, 0x28920, v122
	v_add_u32_e32 v142, 0x28928, v122
	v_add_u32_e32 v124, 0x28940, v122
	v_add_u32_e32 v126, 0x28948, v122
	v_add_u32_e32 v132, 0x28960, v122
	v_add_u32_e32 v134, 0x28968, v122
	v_add_u32_e32 v123, 0x28900, v122
	ds_read2_b32 v[124:125], v124 offset1:1
	ds_read2_b32 v[126:127], v126 offset1:1
	ds_read2_b32 v[132:133], v132 offset1:1
	ds_read2_b32 v[134:135], v134 offset1:1
	ds_read2_b32 v[136:137], v123 offset1:1
	ds_read2_b32 v[138:139], v138 offset1:1
	ds_read2_b32 v[140:141], v140 offset1:1
	ds_read2_b32 v[142:143], v142 offset1:1
	s_waitcnt lgkmcnt(0)
	v_pk_add_f32 v[194:195], v[194:195], v[134:135]
	v_pk_add_f32 v[192:193], v[192:193], v[132:133]
	v_pk_add_f32 v[190:191], v[190:191], v[126:127]
	v_pk_add_f32 v[188:189], v[188:189], v[124:125]
	v_pk_add_f32 v[186:187], v[186:187], v[142:143]
	v_pk_add_f32 v[184:185], v[184:185], v[140:141]
	v_pk_add_f32 v[182:183], v[182:183], v[138:139]
	v_pk_add_f32 v[180:181], v[180:181], v[136:137]
; #define LAS __attribute__((address_space(3)))
; DI void expsum(f32x16& p, float& l_reg, bf16x8& pa0, bf16x8& pa1) {
; #pragma unroll
;     for (int r = 0; r < 16; ++r) p[r] = __builtin_amdgcn_exp2f(p[r]);
;     float ps = 0.f;
; #pragma unroll
;     for (int r = 0; r < 16; ++r) ps += p[r];
;     l_reg += ps; asm volatile("" : "+v"(l_reg));
;     ...
;     ATT_PK4(p, 0, pa0); ATT_PK4(p, 8, pa1);
;     ...
; }
; DI int v_rd_base(int lane) { return ((lane & 3) << 3) | (((lane >> 2) & 3) << 6) | (((lane >> 4) & 1) << 5) | (((lane >> 5) & 1) << 8); }
; template <int OFF> DI s16x4 tr_read(int vb) { s16x4 r; asm volatile("ds_read_b64_tr_b16 %0, %1 offset:%2" : "=&v"(r) : "v"(vb), "i"(OFF) : "memory"); return r; }
; template <int H> DI void v_reads(s16x4* vf, int vb) {
;     vf[0] = tr_read<v_rd_off(0, 2 * H, 0)>(vb); vf[1] = tr_read<v_rd_off(0, 2 * H, 1)>(vb); vf[2] = tr_read<v_rd_off(0, 2 * H + 1, 0)>(vb); vf[3] = tr_read<v_rd_off(0, 2 * H + 1, 1)>(vb);
;     vf[4] = tr_read<v_rd_off(1, 2 * H, 0)>(vb); vf[5] = tr_read<v_rd_off(1, 2 * H, 1)>(vb); vf[6] = tr_read<v_rd_off(1, 2 * H + 1, 0)>(vb); vf[7] = tr_read<v_rd_off(1, 2 * H + 1, 1)>(vb);
;     vf[8] = tr_read<v_rd_off(2, 2 * H, 0)>(vb); vf[9] = tr_read<v_rd_off(2, 2 * H, 1)>(vb); vf[10] = tr_read<v_rd_off(2, 2 * H + 1, 0)>(vb); vf[11] = tr_read<v_rd_off(2, 2 * H + 1, 1)>(vb);
;     vf[12] = tr_read<v_rd_off(3, 2 * H, 0)>(vb); vf[13] = tr_read<v_rd_off(3, 2 * H, 1)>(vb); vf[14] = tr_read<v_rd_off(3, 2 * H + 1, 0)>(vb); vf[15] = tr_read<v_rd_off(3, 2 * H + 1, 1)>(vb);
; }
; DI void pv_mma(f32x16* o, const s16x4* vf, bf16x8 pa0, bf16x8 pa1) {
;     ...
; #pragma unroll
;     for (int d0 = 0; d0 < 4; ++d0) {
;         o[d0] = __builtin_amdgcn_mfma_f32_32x32x16_bf16(pa0, ATT_PK(vf[4 * d0], vf[4 * d0 + 1]), o[d0], 0, 0, 0);
;         o[d0] = __builtin_amdgcn_mfma_f32_32x32x16_bf16(pa1, ATT_PK(vf[4 * d0 + 2], vf[4 * d0 + 3]), o[d0], 0, 0, 0); }
;     ...
; }
; template <int DQK, int D0A, int D0B> DI void k_reads(bf16x8* kf, const LAS unsigned char* Ks, int half, int r32, int hi) {
; #pragma unroll
;     for (int d0 = D0A; d0 < D0B; ++d0) kf[d0 - D0A] = *(const LAS bf16x8*)(Ks + half * (32 * DQK * 2) + kswz<DQK>(r32, (d0 * 16 + hi * 8) * 2));
; }
; template <int D0A, int D0B> DI void qk_mma(f32x16& p, const bf16x8* kf, const bf16x8* qr) {
; #pragma unroll
;     for (int d0 = D0A; d0 < D0B; ++d0) {
.LBB0_1924:
	s_add_i32 s3, s22, 0xffffc000
	s_and_b32 s3, s3, 0x6000
	v_add_u32_e32 v123, s3, v114
	v_add_u32_e32 v140, v123, v118
	v_add_u32_e32 v136, v123, v117
	v_add_u32_e32 v132, v123, v116
	v_add_u32_e32 v123, v123, v115
	ds_read_b128 v[124:127], v123
	ds_read_b128 v[132:135], v132
	ds_read_b128 v[136:139], v136
	ds_read_b128 v[140:143], v140
	ds_read_b64_tr_b16 v[144:145], v121 offset:0x2000
	ds_read_b64_tr_b16 v[146:147], v121 offset:0x2800
	ds_read_b64_tr_b16 v[148:149], v121 offset:0x3000
	ds_read_b64_tr_b16 v[150:151], v121 offset:0x3800
	ds_read_b64_tr_b16 v[152:153], v121 offset:0x2200
	ds_read_b64_tr_b16 v[154:155], v121 offset:0x2a00
	ds_read_b64_tr_b16 v[156:157], v121 offset:0x3200
	ds_read_b64_tr_b16 v[158:159], v121 offset:0x3a00
	ds_read_b64_tr_b16 v[162:163], v121 offset:0x2400
	ds_read_b64_tr_b16 v[164:165], v121 offset:0x2c00
	ds_read_b64_tr_b16 v[166:167], v121 offset:0x3400
	ds_read_b64_tr_b16 v[168:169], v121 offset:0x3c00
	ds_read_b64_tr_b16 v[170:171], v121 offset:0x2600
	ds_read_b64_tr_b16 v[172:173], v121 offset:0x2e00
	ds_read_b64_tr_b16 v[174:175], v121 offset:0x3600
	ds_read_b64_tr_b16 v[176:177], v121 offset:0x3e00
	s_setprio 1
	v_exp_f32_e32 v180, v180
	v_exp_f32_e32 v181, v181
	v_exp_f32_e32 v182, v182
	v_exp_f32_e32 v183, v183
	v_exp_f32_e32 v184, v184
	v_add_f32_e32 v121, 0, v180
	v_exp_f32_e32 v185, v185
	v_add_f32_e32 v121, v181, v121
	v_exp_f32_e32 v186, v186
	v_add_f32_e32 v121, v182, v121
	v_exp_f32_e32 v187, v187
	v_add_f32_e32 v121, v183, v121
	v_exp_f32_e32 v188, v188
	v_add_f32_e32 v121, v184, v121
	v_exp_f32_e32 v189, v189
	v_add_f32_e32 v121, v185, v121
	v_exp_f32_e32 v190, v190
	v_add_f32_e32 v121, v186, v121
	v_exp_f32_e32 v191, v191
	v_add_f32_e32 v121, v187, v121
	v_exp_f32_e32 v192, v192
	v_add_f32_e32 v121, v188, v121
	v_exp_f32_e32 v193, v193
	v_add_f32_e32 v121, v189, v121
	v_exp_f32_e32 v194, v194
	v_add_f32_e32 v121, v190, v121
	v_exp_f32_e32 v195, v195
	v_add_f32_e32 v121, v191, v121
	v_add_f32_e32 v121, v192, v121
	v_add_f32_e32 v121, v193, v121
	v_add_f32_e32 v121, v194, v121
	v_add_f32_e32 v121, v195, v121
	v_add_f32_e32 v120, v120, v121
	v_cvt_pk_bf16_f32 v180, v180, v181
	v_cvt_pk_bf16_f32 v181, v182, v183
	v_cvt_pk_bf16_f32 v182, v184, v185
	v_cvt_pk_bf16_f32 v183, v186, v187
	v_cvt_pk_bf16_f32 v184, v188, v189
	v_cvt_pk_bf16_f32 v185, v190, v191
	v_cvt_pk_bf16_f32 v186, v192, v193
	v_cvt_pk_bf16_f32 v187, v194, v195
	s_nop 0
	v_permlane32_swap_b32_e32 v180, v182
	v_permlane32_swap_b32_e32 v181, v183
	v_permlane32_swap_b32_e32 v184, v186
	v_permlane32_swap_b32_e32 v185, v187
	s_waitcnt lgkmcnt(0)
	s_setprio 0
	s_cmp_lt_u32 s33, 0x100
	s_cbranch_scc1 .Lstg_d0_mid_11
	s_waitcnt vmcnt(3)
	s_barrier
.Lstg_d0_mid_11:
	v_mfma_f32_32x32x16_bf16 v[0:15], v[180:183], v[144:147], v[0:15]
	s_cmp_lt_i32 s0, s55
	s_cselect_b64 s[74:75], -1, 0
	s_cmp_ge_i32 s0, s97
	s_cselect_b64 vcc, -1, 0
	s_or_b64 s[74:75], s[74:75], vcc
	s_and_b64 vcc, exec, s[74:75]
	v_mfma_f32_32x32x16_bf16 v[64:79], v[124:127], v[92:95], 0
	v_mfma_f32_32x32x16_bf16 v[48:63], v[180:183], v[152:155], v[48:63]
	v_mfma_f32_32x32x16_bf16 v[64:79], v[132:135], v[88:91], v[64:79]
	v_mfma_f32_32x32x16_bf16 v[32:47], v[180:183], v[162:165], v[32:47]
	v_mfma_f32_32x32x16_bf16 v[64:79], v[136:139], v[84:87], v[64:79]
	v_mfma_f32_32x32x16_bf16 v[16:31], v[180:183], v[170:173], v[16:31]
	v_mfma_f32_32x32x16_bf16 v[64:79], v[140:143], v[80:83], v[64:79]
	v_mfma_f32_32x32x16_bf16 v[0:15], v[184:187], v[148:151], v[0:15]
	v_mfma_f32_32x32x16_bf16 v[48:63], v[184:187], v[156:159], v[48:63]
	v_mfma_f32_32x32x16_bf16 v[32:47], v[184:187], v[166:169], v[32:47]
	v_mfma_f32_32x32x16_bf16 v[16:31], v[184:187], v[174:177], v[16:31]
	s_cbranch_vccnz .LBB0_1926
	v_add_u32_e32 v136, 0x28988, v122
	v_add_u32_e32 v138, 0x289a0, v122
	v_add_u32_e32 v140, 0x289a8, v122
	v_add_u32_e32 v123, 0x289c0, v122
	v_add_u32_e32 v124, 0x289c8, v122
	v_add_u32_e32 v126, 0x289e0, v122
	v_add_u32_e32 v132, 0x289e8, v122
	v_add_u32_e32 v121, 0x28980, v122
	ds_read2_b32 v[122:123], v123 offset1:1
	ds_read2_b32 v[124:125], v124 offset1:1
	ds_read2_b32 v[126:127], v126 offset1:1
	ds_read2_b32 v[132:133], v132 offset1:1
	ds_read2_b32 v[134:135], v121 offset1:1
	ds_read2_b32 v[136:137], v136 offset1:1
	ds_read2_b32 v[138:139], v138 offset1:1
	ds_read2_b32 v[140:141], v140 offset1:1
	s_waitcnt lgkmcnt(0)
	v_pk_add_f32 v[78:79], v[78:79], v[132:133]
	v_pk_add_f32 v[76:77], v[76:77], v[126:127]
	v_pk_add_f32 v[74:75], v[74:75], v[124:125]
	v_pk_add_f32 v[72:73], v[72:73], v[122:123]
	v_pk_add_f32 v[70:71], v[70:71], v[140:141]
	v_pk_add_f32 v[68:69], v[68:69], v[138:139]
	v_pk_add_f32 v[66:67], v[66:67], v[136:137]
	v_pk_add_f32 v[64:65], v[64:65], v[134:135]

; #define LAS __attribute__((address_space(3)))
; DI void expsum(f32x16& p, float& l_reg, bf16x8& pa0, bf16x8& pa1) {
; #pragma unroll
;     for (int r = 0; r < 16; ++r) p[r] = __builtin_amdgcn_exp2f(p[r]);
;     float ps = 0.f;
; #pragma unroll
;     for (int r = 0; r < 16; ++r) ps += p[r];
;     l_reg += ps; asm volatile("" : "+v"(l_reg));
;     ...
;     ATT_PK4(p, 0, pa0); ATT_PK4(p, 8, pa1);
;     ...
; }
; DI int v_rd_base(int lane) { return ((lane & 3) << 3) | (((lane >> 2) & 3) << 6) | (((lane >> 4) & 1) << 5) | (((lane >> 5) & 1) << 8); }
; template <int OFF> DI s16x4 tr_read(int vb) { s16x4 r; asm volatile("ds_read_b64_tr_b16 %0, %1 offset:%2" : "=&v"(r) : "v"(vb), "i"(OFF) : "memory"); return r; }
; template <int H> DI void v_reads(s16x4* vf, int vb) {
;     vf[0] = tr_read<v_rd_off(0, 2 * H, 0)>(vb); vf[1] = tr_read<v_rd_off(0, 2 * H, 1)>(vb); vf[2] = tr_read<v_rd_off(0, 2 * H + 1, 0)>(vb); vf[3] = tr_read<v_rd_off(0, 2 * H + 1, 1)>(vb);
;     vf[4] = tr_read<v_rd_off(1, 2 * H, 0)>(vb); vf[5] = tr_read<v_rd_off(1, 2 * H, 1)>(vb); vf[6] = tr_read<v_rd_off(1, 2 * H + 1, 0)>(vb); vf[7] = tr_read<v_rd_off(1, 2 * H + 1, 1)>(vb);
;     vf[8] = tr_read<v_rd_off(2, 2 * H, 0)>(vb); vf[9] = tr_read<v_rd_off(2, 2 * H, 1)>(vb); vf[10] = tr_read<v_rd_off(2, 2 * H + 1, 0)>(vb); vf[11] = tr_read<v_rd_off(2, 2 * H + 1, 1)>(vb);
;     vf[12] = tr_read<v_rd_off(3, 2 * H, 0)>(vb); vf[13] = tr_read<v_rd_off(3, 2 * H, 1)>(vb); vf[14] = tr_read<v_rd_off(3, 2 * H + 1, 0)>(vb); vf[15] = tr_read<v_rd_off(3, 2 * H + 1, 1)>(vb);
; }
; DI void pv_mma(f32x16* o, const s16x4* vf, bf16x8 pa0, bf16x8 pa1) {
;     ...
; #pragma unroll
;     for (int d0 = 0; d0 < 4; ++d0) {
;         o[d0] = __builtin_amdgcn_mfma_f32_32x32x16_bf16(pa0, ATT_PK(vf[4 * d0], vf[4 * d0 + 1]), o[d0], 0, 0, 0);
;         o[d0] = __builtin_amdgcn_mfma_f32_32x32x16_bf16(pa1, ATT_PK(vf[4 * d0 + 2], vf[4 * d0 + 3]), o[d0], 0, 0, 0); }
;     ...
; }
; template <int DQK, int D0A, int D0B> DI void k_reads(bf16x8* kf, const LAS unsigned char* Ks, int half, int r32, int hi) {
; #pragma unroll
;     for (int d0 = D0A; d0 < D0B; ++d0) kf[d0 - D0A] = *(const LAS bf16x8*)(Ks + half * (32 * DQK * 2) + kswz<DQK>(r32, (d0 * 16 + hi * 8) * 2));
; }
; template <int D0A, int D0B> DI void qk_mma(f32x16& p, const bf16x8* kf, const bf16x8* qr) {
; #pragma unroll
;     for (int d0 = D0A; d0 < D0B; ++d0) {
.LBB0_1953:
	s_add_i32 s3, s0, -1
	s_add_i32 s2, s22, 0xffffa000
	s_and_b32 s2, s2, 0x6000
	v_add_u32_e32 v121, s2, v114
	v_add_u32_e32 v122, v121, v115
	v_add_u32_e32 v126, v121, v116
	ds_read_b128 v[122:125], v122 offset:4096
	ds_read_b128 v[132:135], v126 offset:4096
	v_add_u32_e32 v126, v121, v117
	v_add_u32_e32 v121, v121, v118
	s_lshl_b32 s2, s23, 14
	ds_read_b128 v[136:139], v126 offset:4096
	ds_read_b128 v[140:143], v121 offset:4096
	v_add_u32_e32 v121, s2, v106
	ds_read_b64_tr_b16 v[144:145], v121 offset:0
	ds_read_b64_tr_b16 v[146:147], v121 offset:0x800
	ds_read_b64_tr_b16 v[148:149], v121 offset:0x1000
	ds_read_b64_tr_b16 v[150:151], v121 offset:0x1800
	ds_read_b64_tr_b16 v[152:153], v121 offset:0x200
	ds_read_b64_tr_b16 v[154:155], v121 offset:0xa00
	ds_read_b64_tr_b16 v[156:157], v121 offset:0x1200
	ds_read_b64_tr_b16 v[158:159], v121 offset:0x1a00
	ds_read_b64_tr_b16 v[162:163], v121 offset:0x400
	ds_read_b64_tr_b16 v[164:165], v121 offset:0xc00
	ds_read_b64_tr_b16 v[166:167], v121 offset:0x1400
	ds_read_b64_tr_b16 v[168:169], v121 offset:0x1c00
	ds_read_b64_tr_b16 v[170:171], v121 offset:0x600
	ds_read_b64_tr_b16 v[172:173], v121 offset:0xe00
	ds_read_b64_tr_b16 v[174:175], v121 offset:0x1600
	ds_read_b64_tr_b16 v[176:177], v121 offset:0x1e00
	s_setprio 1
	v_exp_f32_e32 v64, v64
	v_exp_f32_e32 v65, v65
	v_exp_f32_e32 v66, v66
	v_exp_f32_e32 v67, v67
	v_exp_f32_e32 v68, v68
	v_add_f32_e32 v126, 0, v64
	v_exp_f32_e32 v69, v69
	v_add_f32_e32 v126, v65, v126
	v_exp_f32_e32 v70, v70
	v_add_f32_e32 v126, v66, v126
	v_exp_f32_e32 v71, v71
	v_add_f32_e32 v126, v67, v126
	v_exp_f32_e32 v72, v72
	v_add_f32_e32 v126, v68, v126
	v_exp_f32_e32 v73, v73
	v_add_f32_e32 v126, v69, v126
	v_exp_f32_e32 v74, v74
	v_add_f32_e32 v126, v70, v126
	v_exp_f32_e32 v75, v75
	v_add_f32_e32 v126, v71, v126
	v_exp_f32_e32 v76, v76
	v_add_f32_e32 v126, v72, v126
	v_exp_f32_e32 v77, v77
	v_add_f32_e32 v126, v73, v126
	v_exp_f32_e32 v78, v78
	v_add_f32_e32 v126, v74, v126
	v_exp_f32_e32 v79, v79
	v_add_f32_e32 v126, v75, v126
	v_add_f32_e32 v126, v76, v126
	v_add_f32_e32 v126, v77, v126
	v_add_f32_e32 v126, v78, v126
	v_add_f32_e32 v126, v79, v126
	v_add_f32_e32 v120, v126, v120
	v_cvt_pk_bf16_f32 v64, v64, v65
	v_cvt_pk_bf16_f32 v65, v66, v67
	v_cvt_pk_bf16_f32 v66, v68, v69
	v_cvt_pk_bf16_f32 v67, v70, v71
	v_cvt_pk_bf16_f32 v68, v72, v73
	v_cvt_pk_bf16_f32 v69, v74, v75
	v_cvt_pk_bf16_f32 v70, v76, v77
	v_cvt_pk_bf16_f32 v71, v78, v79
	s_nop 0
	v_permlane32_swap_b32_e32 v64, v66
	v_permlane32_swap_b32_e32 v65, v67
	v_permlane32_swap_b32_e32 v68, v70
	v_permlane32_swap_b32_e32 v69, v71
	s_waitcnt lgkmcnt(0)
	s_setprio 0
	v_mfma_f32_32x32x16_bf16 v[0:15], v[64:67], v[144:147], v[0:15]
	s_cmp_lt_i32 s3, s47
	s_cselect_b64 s[74:75], -1, 0
	s_cmp_ge_i32 s3, s52
	s_cselect_b64 s[90:91], -1, 0
	s_or_b64 s[74:75], s[74:75], s[90:91]
	s_and_b64 vcc, exec, s[74:75]
	v_mfma_f32_32x32x16_bf16 v[180:195], v[122:125], v[92:95], 0
	v_mfma_f32_32x32x16_bf16 v[48:63], v[64:67], v[152:155], v[48:63]
	v_mfma_f32_32x32x16_bf16 v[180:195], v[132:135], v[88:91], v[180:195]
	v_mfma_f32_32x32x16_bf16 v[16:31], v[64:67], v[162:165], v[16:31]
	v_mfma_f32_32x32x16_bf16 v[180:195], v[136:139], v[84:87], v[180:195]
	v_mfma_f32_32x32x16_bf16 v[32:47], v[64:67], v[170:173], v[32:47]
	v_mfma_f32_32x32x16_bf16 v[180:195], v[140:143], v[80:83], v[180:195]
	v_mfma_f32_32x32x16_bf16 v[0:15], v[68:71], v[148:151], v[0:15]
	v_mfma_f32_32x32x16_bf16 v[48:63], v[68:71], v[156:159], v[48:63]
	v_mfma_f32_32x32x16_bf16 v[16:31], v[68:71], v[166:169], v[16:31]
	v_mfma_f32_32x32x16_bf16 v[32:47], v[68:71], v[174:177], v[32:47]
	v_add_u32_e32 v122, s7, v119
	s_cbranch_vccnz .LBB0_1955
	v_add_u32_e32 v138, 0x28908, v122
	v_add_u32_e32 v140, 0x28920, v122
	v_add_u32_e32 v142, 0x28928, v122
	v_add_u32_e32 v124, 0x28940, v122
	v_add_u32_e32 v126, 0x28948, v122
	v_add_u32_e32 v132, 0x28960, v122
	v_add_u32_e32 v134, 0x28968, v122
	v_add_u32_e32 v123, 0x28900, v122
	ds_read2_b32 v[124:125], v124 offset1:1
	ds_read2_b32 v[126:127], v126 offset1:1
	ds_read2_b32 v[132:133], v132 offset1:1
	ds_read2_b32 v[134:135], v134 offset1:1
	ds_read2_b32 v[136:137], v123 offset1:1
	ds_read2_b32 v[138:139], v138 offset1:1
	ds_read2_b32 v[140:141], v140 offset1:1
	ds_read2_b32 v[142:143], v142 offset1:1
	s_waitcnt lgkmcnt(0)
	v_pk_add_f32 v[194:195], v[194:195], v[134:135]
	v_pk_add_f32 v[192:193], v[192:193], v[132:133]
	v_pk_add_f32 v[190:191], v[190:191], v[126:127]
	v_pk_add_f32 v[188:189], v[188:189], v[124:125]
	v_pk_add_f32 v[186:187], v[186:187], v[142:143]
	v_pk_add_f32 v[184:185], v[184:185], v[140:141]
	v_pk_add_f32 v[182:183], v[182:183], v[138:139]
	v_pk_add_f32 v[180:181], v[180:181], v[136:137]

; #define LAS __attribute__((address_space(3)))
; DI int v_rd_base(int lane) { return ((lane & 3) << 3) | (((lane >> 2) & 3) << 6) | (((lane >> 4) & 1) << 5) | (((lane >> 5) & 1) << 8); }
; DI void pv_mma(f32x16* o, const s16x4* vf, bf16x8 pa0, bf16x8 pa1) {
;     ...
; #pragma unroll
;     for (int d0 = 0; d0 < 4; ++d0) {
;         o[d0] = __builtin_amdgcn_mfma_f32_32x32x16_bf16(pa0, ATT_PK(vf[4 * d0], vf[4 * d0 + 1]), o[d0], 0, 0, 0);
;         o[d0] = __builtin_amdgcn_mfma_f32_32x32x16_bf16(pa1, ATT_PK(vf[4 * d0 + 2], vf[4 * d0 + 3]), o[d0], 0, 0, 0); }
;     ...
; }
; template <int DQK, int D0A, int D0B> DI void k_reads(bf16x8* kf, const LAS unsigned char* Ks, int half, int r32, int hi) {
; #pragma unroll
;     for (int d0 = D0A; d0 < D0B; ++d0) kf[d0 - D0A] = *(const LAS bf16x8*)(Ks + half * (32 * DQK * 2) + kswz<DQK>(r32, (d0 * 16 + hi * 8) * 2));
; }
; template <int D0A, int D0B> DI void qk_mma(f32x16& p, const bf16x8* kf, const bf16x8* qr) {
; #pragma unroll
;     for (int d0 = D0A; d0 < D0B; ++d0) {
;         if (d0 == 0) { f32x16 z; _Pragma("unroll") for (int r = 0; r < 16; ++r) z[r] = 0.f; p = __builtin_amdgcn_mfma_f32_32x32x16_bf16(kf[0], qr[0], z, 0, 0, 0); }
;         else p = __builtin_amdgcn_mfma_f32_32x32x16_bf16(kf[d0 - D0A], qr[d0], p, 0, 0, 0); }
; }
; template <int DQK, int MODE, int LDQ, int LDK, int LDV> ...
;     ...
;     const int vbase = (int)(unsigned)(size_t)lds + V_OFF + v_rd_base(lane);
;     ...
;     constexpr int NDA = ND0 > 6 ? 6 : ND0;
.Lstg_d1_mid_19:
	v_mfma_f32_32x32x16_bf16 v[0:15], v[180:183], v[144:147], v[0:15]
	s_cmp_lt_i32 s0, s47
	s_cselect_b64 s[74:75], -1, 0
	s_cmp_ge_i32 s0, s52
	s_cselect_b64 s[90:91], -1, 0
	s_or_b64 s[74:75], s[74:75], s[90:91]
	s_and_b64 vcc, exec, s[74:75]
	v_mfma_f32_32x32x16_bf16 v[64:79], v[124:127], v[92:95], 0
	v_mfma_f32_32x32x16_bf16 v[48:63], v[180:183], v[152:155], v[48:63]
	v_mfma_f32_32x32x16_bf16 v[64:79], v[132:135], v[88:91], v[64:79]
	v_mfma_f32_32x32x16_bf16 v[16:31], v[180:183], v[162:165], v[16:31]
	v_mfma_f32_32x32x16_bf16 v[64:79], v[136:139], v[84:87], v[64:79]
	v_mfma_f32_32x32x16_bf16 v[32:47], v[180:183], v[170:173], v[32:47]
	v_mfma_f32_32x32x16_bf16 v[64:79], v[140:143], v[80:83], v[64:79]
	v_mfma_f32_32x32x16_bf16 v[0:15], v[184:187], v[148:151], v[0:15]
	v_mfma_f32_32x32x16_bf16 v[48:63], v[184:187], v[156:159], v[48:63]
	v_mfma_f32_32x32x16_bf16 v[16:31], v[184:187], v[166:169], v[16:31]
	v_mfma_f32_32x32x16_bf16 v[32:47], v[184:187], v[174:177], v[32:47]
	s_cbranch_vccnz .LBB0_1957
	v_add_u32_e32 v136, 0x28988, v122
	v_add_u32_e32 v138, 0x289a0, v122
	v_add_u32_e32 v140, 0x289a8, v122
	v_add_u32_e32 v123, 0x289c0, v122
	v_add_u32_e32 v124, 0x289c8, v122
	v_add_u32_e32 v126, 0x289e0, v122
	v_add_u32_e32 v132, 0x289e8, v122
	v_add_u32_e32 v121, 0x28980, v122
	ds_read2_b32 v[122:123], v123 offset1:1
	ds_read2_b32 v[124:125], v124 offset1:1
	ds_read2_b32 v[126:127], v126 offset1:1
	ds_read2_b32 v[132:133], v132 offset1:1
	ds_read2_b32 v[134:135], v121 offset1:1
	ds_read2_b32 v[136:137], v136 offset1:1
	ds_read2_b32 v[138:139], v138 offset1:1
	ds_read2_b32 v[140:141], v140 offset1:1
	s_waitcnt lgkmcnt(0)
	v_pk_add_f32 v[78:79], v[78:79], v[132:133]
	v_pk_add_f32 v[76:77], v[76:77], v[126:127]
	v_pk_add_f32 v[74:75], v[74:75], v[124:125]
	v_pk_add_f32 v[72:73], v[72:73], v[122:123]
	v_pk_add_f32 v[70:71], v[70:71], v[140:141]
	v_pk_add_f32 v[68:69], v[68:69], v[138:139]
	v_pk_add_f32 v[66:67], v[66:67], v[136:137]
	v_pk_add_f32 v[64:65], v[64:65], v[134:135]
